# LN normalize: 57 pairs of x-mean v_sub packed into v_pk_add_f32 with neg (on packed SwiGLU version)
# baseline (speedup 1.0000x reference)
.LBB0_722:
	s_or_b64 exec, exec, s[50:51]
	v_lshlrev_b64 v[128:129], 2, v[186:187]
	s_waitcnt lgkmcnt(0)
	s_barrier
	v_lshl_add_u64 v[132:133], s[30:31], 0, v[128:129]
	v_lshl_add_u64 v[140:141], s[34:35], 0, v[128:129]
	s_waitcnt lgkmcnt(0)
	global_load_dwordx4 v[128:131], v[132:133], off offset:528
	global_load_dwordx4 v[136:139], v[132:133], off offset:512
	s_nop 0
	global_load_dwordx4 v[132:135], v[140:141], off offset:528
	s_nop 0
	global_load_dwordx4 v[140:143], v[140:141], off offset:512
	ds_read_b64 v[160:161], v209
	v_lshlrev_b64 v[162:163], 10, v[188:189]
	v_lshl_add_u64 v[162:163], v[162:163], 0, v[186:187]
	s_and_b64 vcc, exec, s[44:45]
	v_lshl_add_u64 v[164:165], v[162:163], 2, s[28:29]
	s_waitcnt lgkmcnt(0)
	v_pk_add_f32 v[74:75], v[74:75], v[160:161] op_sel_hi:[1,0] neg_lo:[0,1] neg_hi:[0,1]
	v_pk_add_f32 v[72:73], v[72:73], v[160:161] op_sel_hi:[1,0] neg_lo:[0,1] neg_hi:[0,1]
	v_pk_add_f32 v[70:71], v[70:71], v[160:161] op_sel_hi:[1,0] neg_lo:[0,1] neg_hi:[0,1]
	v_pk_add_f32 v[68:69], v[68:69], v[160:161] op_sel_hi:[1,0] neg_lo:[0,1] neg_hi:[0,1]
	v_pk_mul_f32 v[72:73], v[160:161], v[72:73] op_sel:[1,0]
	v_pk_mul_f32 v[74:75], v[160:161], v[74:75] op_sel:[1,0]
	v_pk_mul_f32 v[68:69], v[160:161], v[68:69] op_sel:[1,0]
	v_pk_mul_f32 v[70:71], v[160:161], v[70:71] op_sel:[1,0]
	s_waitcnt vmcnt(5)
	v_pk_fma_f32 v[68:69], v[144:145], v[68:69], v[148:149]
	s_waitcnt vmcnt(4)
	v_pk_fma_f32 v[74:75], v[154:155], v[74:75], v[158:159]
	v_pk_fma_f32 v[72:73], v[152:153], v[72:73], v[156:157]
	v_pk_fma_f32 v[70:71], v[146:147], v[70:71], v[150:151]
	s_cbranch_vccz .LBB0_724
	global_store_dwordx4 v[164:165], v[72:75], off
	global_store_dwordx4 v[164:165], v[68:71], off offset:16
.LBB0_724:
	v_mov_b32_e32 v166, v161
	v_mov_b32_e32 v167, v161
	v_cvt_pk_bf16_f32 v72, v72, v73
	v_cvt_pk_bf16_f32 v73, v74, v75
	v_cvt_pk_bf16_f32 v75, v70, v71
	v_readlane_b32 s12, v253, 52
	v_pk_add_f32 v[22:23], v[22:23], v[160:161] op_sel_hi:[1,0] neg_lo:[0,1] neg_hi:[0,1]
	v_pk_add_f32 v[20:21], v[20:21], v[160:161] op_sel_hi:[1,0] neg_lo:[0,1] neg_hi:[0,1]
	v_mov_b32_e32 v70, v161
	v_mov_b32_e32 v71, v161
	v_pk_add_f32 v[18:19], v[18:19], v[160:161] op_sel_hi:[1,0] neg_lo:[0,1] neg_hi:[0,1]
	v_pk_add_f32 v[16:17], v[16:17], v[160:161] op_sel_hi:[1,0] neg_lo:[0,1] neg_hi:[0,1]
	v_readlane_b32 s13, v253, 53
	v_pk_mul_f32 v[20:21], v[166:167], v[20:21]
	v_pk_mul_f32 v[22:23], v[70:71], v[22:23]
	v_pk_mul_f32 v[16:17], v[166:167], v[16:17]
	v_pk_mul_f32 v[18:19], v[70:71], v[18:19]
	v_cndmask_b32_e64 v70, 0, 1, s[44:45]
	v_cvt_pk_bf16_f32 v74, v68, v69
	v_lshl_add_u64 v[68:69], v[162:163], 1, s[12:13]
	s_waitcnt vmcnt(0)
	v_pk_fma_f32 v[22:23], v[138:139], v[22:23], v[142:143]
	v_pk_fma_f32 v[20:21], v[136:137], v[20:21], v[140:141]
	v_pk_fma_f32 v[18:19], v[130:131], v[18:19], v[134:135]
	v_cmp_ne_u32_e64 s[12:13], 1, v70
	s_andn2_b64 vcc, exec, s[44:45]
	v_pk_fma_f32 v[16:17], v[128:129], v[16:17], v[132:133]
	global_store_dwordx4 v[68:69], v[72:75], off
	s_cbranch_vccnz .LBB0_726
	global_store_dwordx4 v[164:165], v[20:23], off offset:512
	global_store_dwordx4 v[164:165], v[16:19], off offset:528
.LBB0_726:
	s_nop 0
	v_cvt_pk_bf16_f32 v20, v20, v21
	v_cvt_pk_bf16_f32 v21, v22, v23
	v_cvt_pk_bf16_f32 v22, v16, v17
	ds_read_b64 v[16:17], v211
	v_cvt_pk_bf16_f32 v23, v18, v19
	v_add_u32_e32 v18, s54, v210
	v_ashrrev_i32_e32 v19, 31, v18
	v_lshlrev_b64 v[18:19], 10, v[18:19]
	s_waitcnt lgkmcnt(0)
	v_pk_add_f32 v[14:15], v[14:15], v[16:17] op_sel_hi:[1,0] neg_lo:[0,1] neg_hi:[0,1]
	v_pk_add_f32 v[12:13], v[12:13], v[16:17] op_sel_hi:[1,0] neg_lo:[0,1] neg_hi:[0,1]
	v_pk_add_f32 v[10:11], v[10:11], v[16:17] op_sel_hi:[1,0] neg_lo:[0,1] neg_hi:[0,1]
	v_pk_add_f32 v[8:9], v[8:9], v[16:17] op_sel_hi:[1,0] neg_lo:[0,1] neg_hi:[0,1]
	global_store_dwordx4 v[68:69], v[20:23], off offset:256
	v_pk_mul_f32 v[12:13], v[16:17], v[12:13] op_sel:[1,0]
	v_pk_mul_f32 v[14:15], v[16:17], v[14:15] op_sel:[1,0]
	v_lshl_add_u64 v[20:21], v[18:19], 0, v[186:187]
	v_pk_mul_f32 v[8:9], v[16:17], v[8:9] op_sel:[1,0]
	v_pk_mul_f32 v[10:11], v[16:17], v[10:11] op_sel:[1,0]
	v_pk_fma_f32 v[14:15], v[154:155], v[14:15], v[158:159]
	v_pk_fma_f32 v[12:13], v[152:153], v[12:13], v[156:157]
	v_pk_fma_f32 v[10:11], v[146:147], v[10:11], v[150:151]
	v_pk_fma_f32 v[8:9], v[144:145], v[8:9], v[148:149]
	s_and_b64 vcc, exec, s[12:13]
	v_lshl_add_u64 v[18:19], v[20:21], 2, s[28:29]
	s_cbranch_vccnz .LBB0_728
	global_store_dwordx4 v[18:19], v[12:15], off
	global_store_dwordx4 v[18:19], v[8:11], off offset:16
.LBB0_728:
	v_mov_b32_e32 v22, v17
	v_mov_b32_e32 v23, v17
	v_cvt_pk_bf16_f32 v12, v12, v13
	v_cvt_pk_bf16_f32 v13, v14, v15
	v_cvt_pk_bf16_f32 v15, v10, v11
	v_readlane_b32 s50, v253, 52
	v_pk_add_f32 v[6:7], v[6:7], v[16:17] op_sel_hi:[1,0] neg_lo:[0,1] neg_hi:[0,1]
	v_pk_add_f32 v[4:5], v[4:5], v[16:17] op_sel_hi:[1,0] neg_lo:[0,1] neg_hi:[0,1]
	v_mov_b32_e32 v10, v17
	v_mov_b32_e32 v11, v17
	v_pk_add_f32 v[2:3], v[2:3], v[16:17] op_sel_hi:[1,0] neg_lo:[0,1] neg_hi:[0,1]
	v_pk_add_f32 v[0:1], v[0:1], v[16:17] op_sel_hi:[1,0] neg_lo:[0,1] neg_hi:[0,1]
	v_readlane_b32 s51, v253, 53
	v_pk_mul_f32 v[4:5], v[22:23], v[4:5]
	v_pk_mul_f32 v[6:7], v[10:11], v[6:7]
	v_pk_mul_f32 v[0:1], v[22:23], v[0:1]
	v_pk_mul_f32 v[2:3], v[10:11], v[2:3]
	v_cvt_pk_bf16_f32 v14, v8, v9
	v_lshl_add_u64 v[8:9], v[20:21], 1, s[50:51]
	v_pk_fma_f32 v[6:7], v[138:139], v[6:7], v[142:143]
	v_pk_fma_f32 v[4:5], v[136:137], v[4:5], v[140:141]
	v_pk_fma_f32 v[2:3], v[130:131], v[2:3], v[134:135]
	s_and_b64 vcc, exec, s[12:13]
	v_pk_fma_f32 v[0:1], v[128:129], v[0:1], v[132:133]
	global_store_dwordx4 v[8:9], v[12:15], off
	s_cbranch_vccnz .LBB0_730
	global_store_dwordx4 v[18:19], v[4:7], off offset:512
	global_store_dwordx4 v[18:19], v[0:3], off offset:528
.LBB0_730:
	s_nop 0
	v_cvt_pk_bf16_f32 v4, v4, v5
	v_cvt_pk_bf16_f32 v5, v6, v7
	v_cvt_pk_bf16_f32 v6, v0, v1
	v_cvt_pk_bf16_f32 v7, v2, v3
	global_store_dwordx4 v[8:9], v[4:7], off offset:256
	ds_read_b64 v[8:9], v213
	v_add_u32_e32 v0, s54, v212
	v_ashrrev_i32_e32 v1, 31, v0
	v_lshlrev_b64 v[0:1], 10, v[0:1]
	v_lshl_add_u64 v[12:13], v[0:1], 0, v[186:187]
	s_waitcnt lgkmcnt(0)
	v_pk_add_f32 v[0:1], v[62:63], v[8:9] op_sel_hi:[1,0] neg_lo:[0,1] neg_hi:[0,1]
	v_pk_add_f32 v[2:3], v[60:61], v[8:9] op_sel_hi:[1,0] neg_lo:[0,1] neg_hi:[0,1]
	v_pk_mul_f32 v[4:5], v[8:9], v[2:3] op_sel:[1,0]
	v_pk_mul_f32 v[0:1], v[8:9], v[0:1] op_sel:[1,0]
	v_sub_f32_e32 v7, v57, v8
	v_pk_fma_f32 v[2:3], v[154:155], v[0:1], v[158:159]
	v_pk_fma_f32 v[0:1], v[152:153], v[4:5], v[156:157]
	v_pk_add_f32 v[4:5], v[58:59], v[8:9] op_sel_hi:[1,0] neg_lo:[0,1] neg_hi:[0,1]
	v_sub_f32_e32 v6, v56, v8
	v_pk_mul_f32 v[10:11], v[8:9], v[6:7] op_sel:[1,0]
	v_pk_mul_f32 v[4:5], v[8:9], v[4:5] op_sel:[1,0]
	s_and_b64 vcc, exec, s[12:13]
	v_pk_fma_f32 v[6:7], v[146:147], v[4:5], v[150:151]
	v_pk_fma_f32 v[4:5], v[144:145], v[10:11], v[148:149]
	v_lshl_add_u64 v[10:11], v[12:13], 2, s[28:29]
	s_cbranch_vccnz .LBB0_732
	global_store_dwordx4 v[10:11], v[0:3], off
	global_store_dwordx4 v[10:11], v[4:7], off offset:16
.LBB0_732:
	v_readlane_b32 s50, v253, 52
	v_readlane_b32 s51, v253, 53
	v_cvt_pk_bf16_f32 v0, v0, v1
	v_cvt_pk_bf16_f32 v1, v2, v3
	v_cvt_pk_bf16_f32 v2, v4, v5
	v_cvt_pk_bf16_f32 v3, v6, v7
	v_lshl_add_u64 v[12:13], v[12:13], 1, s[50:51]
	v_mov_b32_e32 v14, v9
	v_mov_b32_e32 v15, v9
	global_store_dwordx4 v[12:13], v[0:3], off
	v_mov_b32_e32 v6, v9
	v_mov_b32_e32 v7, v9
	v_pk_add_f32 v[0:1], v[46:47], v[8:9] op_sel_hi:[1,0] neg_lo:[0,1] neg_hi:[0,1]
	v_pk_add_f32 v[2:3], v[44:45], v[8:9] op_sel_hi:[1,0] neg_lo:[0,1] neg_hi:[0,1]
	v_pk_mul_f32 v[4:5], v[14:15], v[2:3]
	v_pk_mul_f32 v[0:1], v[6:7], v[0:1]
	v_sub_f32_e32 v9, v41, v8
	v_pk_fma_f32 v[2:3], v[138:139], v[0:1], v[142:143]
	v_pk_fma_f32 v[0:1], v[136:137], v[4:5], v[140:141]
	v_pk_add_f32 v[4:5], v[42:43], v[8:9] op_sel_hi:[1,0] neg_lo:[0,1] neg_hi:[0,1]
	v_sub_f32_e32 v8, v40, v8
	v_pk_mul_f32 v[8:9], v[14:15], v[8:9]
	v_pk_mul_f32 v[4:5], v[6:7], v[4:5]
	s_and_b64 vcc, exec, s[12:13]
	v_pk_fma_f32 v[6:7], v[130:131], v[4:5], v[134:135]
	v_pk_fma_f32 v[4:5], v[128:129], v[8:9], v[132:133]
	s_cbranch_vccnz .LBB0_734
	global_store_dwordx4 v[10:11], v[0:3], off offset:512
	global_store_dwordx4 v[10:11], v[4:7], off offset:528
.LBB0_734:
	ds_read_b64 v[8:9], v215
	v_cvt_pk_bf16_f32 v0, v0, v1
	v_cvt_pk_bf16_f32 v1, v2, v3
	v_cvt_pk_bf16_f32 v2, v4, v5
	v_cvt_pk_bf16_f32 v3, v6, v7
	global_store_dwordx4 v[12:13], v[0:3], off offset:256
	s_waitcnt lgkmcnt(0)
	v_pk_add_f32 v[6:7], v[32:33], v[8:9] op_sel_hi:[1,0] neg_lo:[0,1] neg_hi:[0,1]
	v_add_u32_e32 v0, s54, v214
	v_ashrrev_i32_e32 v1, 31, v0
	v_lshlrev_b64 v[0:1], 10, v[0:1]
	v_lshl_add_u64 v[12:13], v[0:1], 0, v[186:187]
	v_pk_add_f32 v[0:1], v[38:39], v[8:9] op_sel_hi:[1,0] neg_lo:[0,1] neg_hi:[0,1]
	v_pk_add_f32 v[2:3], v[36:37], v[8:9] op_sel_hi:[1,0] neg_lo:[0,1] neg_hi:[0,1]
	v_pk_mul_f32 v[4:5], v[8:9], v[2:3] op_sel:[1,0]
	v_pk_mul_f32 v[0:1], v[8:9], v[0:1] op_sel:[1,0]
	v_pk_mul_f32 v[10:11], v[8:9], v[6:7] op_sel:[1,0]
	v_pk_fma_f32 v[2:3], v[154:155], v[0:1], v[158:159]
	v_pk_fma_f32 v[0:1], v[152:153], v[4:5], v[156:157]
	v_pk_add_f32 v[4:5], v[34:35], v[8:9] op_sel_hi:[1,0] neg_lo:[0,1] neg_hi:[0,1]
	v_pk_mul_f32 v[4:5], v[8:9], v[4:5] op_sel:[1,0]
	s_and_b64 vcc, exec, s[12:13]
	v_pk_fma_f32 v[6:7], v[146:147], v[4:5], v[150:151]
	v_pk_fma_f32 v[4:5], v[144:145], v[10:11], v[148:149]
	v_lshl_add_u64 v[10:11], v[12:13], 2, s[28:29]
	s_cbranch_vccnz .LBB0_736
	global_store_dwordx4 v[10:11], v[0:3], off
	global_store_dwordx4 v[10:11], v[4:7], off offset:16
.LBB0_736:
	v_readlane_b32 s50, v253, 52
	v_readlane_b32 s51, v253, 53
	v_cvt_pk_bf16_f32 v0, v0, v1
	v_cvt_pk_bf16_f32 v1, v2, v3
	v_cvt_pk_bf16_f32 v2, v4, v5
	v_cvt_pk_bf16_f32 v3, v6, v7
	v_lshl_add_u64 v[12:13], v[12:13], 1, s[50:51]
	v_mov_b32_e32 v14, v9
	v_mov_b32_e32 v15, v9
	global_store_dwordx4 v[12:13], v[0:3], off
	v_mov_b32_e32 v6, v9
	v_mov_b32_e32 v7, v9
	v_pk_add_f32 v[0:1], v[30:31], v[8:9] op_sel_hi:[1,0] neg_lo:[0,1] neg_hi:[0,1]
	v_pk_add_f32 v[2:3], v[28:29], v[8:9] op_sel_hi:[1,0] neg_lo:[0,1] neg_hi:[0,1]
	v_pk_mul_f32 v[4:5], v[14:15], v[2:3]
	v_pk_mul_f32 v[0:1], v[6:7], v[0:1]
	v_sub_f32_e32 v9, v25, v8
	v_pk_fma_f32 v[2:3], v[138:139], v[0:1], v[142:143]
	v_pk_fma_f32 v[0:1], v[136:137], v[4:5], v[140:141]
	v_pk_add_f32 v[4:5], v[26:27], v[8:9] op_sel_hi:[1,0] neg_lo:[0,1] neg_hi:[0,1]
	v_sub_f32_e32 v8, v24, v8
	v_pk_mul_f32 v[8:9], v[14:15], v[8:9]
	v_pk_mul_f32 v[4:5], v[6:7], v[4:5]
	s_and_b64 vcc, exec, s[12:13]
	v_pk_fma_f32 v[6:7], v[130:131], v[4:5], v[134:135]
	v_pk_fma_f32 v[4:5], v[128:129], v[8:9], v[132:133]
	s_cbranch_vccnz .LBB0_738
	global_store_dwordx4 v[10:11], v[0:3], off offset:512
	global_store_dwordx4 v[10:11], v[4:7], off offset:528
.LBB0_738:
	ds_read_b64 v[8:9], v217
	v_cvt_pk_bf16_f32 v0, v0, v1
	v_cvt_pk_bf16_f32 v1, v2, v3
	v_cvt_pk_bf16_f32 v2, v4, v5
	v_cvt_pk_bf16_f32 v3, v6, v7
	global_store_dwordx4 v[12:13], v[0:3], off offset:256
	s_waitcnt lgkmcnt(0)
	v_pk_add_f32 v[6:7], v[88:89], v[8:9] op_sel_hi:[1,0] neg_lo:[0,1] neg_hi:[0,1]
	v_add_u32_e32 v0, s54, v216
	v_ashrrev_i32_e32 v1, 31, v0
	v_lshlrev_b64 v[0:1], 10, v[0:1]
	v_lshl_add_u64 v[12:13], v[0:1], 0, v[186:187]
	v_pk_add_f32 v[0:1], v[94:95], v[8:9] op_sel_hi:[1,0] neg_lo:[0,1] neg_hi:[0,1]
	v_pk_add_f32 v[2:3], v[92:93], v[8:9] op_sel_hi:[1,0] neg_lo:[0,1] neg_hi:[0,1]
	v_pk_mul_f32 v[4:5], v[8:9], v[2:3] op_sel:[1,0]
	v_pk_mul_f32 v[0:1], v[8:9], v[0:1] op_sel:[1,0]
	v_pk_mul_f32 v[10:11], v[8:9], v[6:7] op_sel:[1,0]
	v_pk_fma_f32 v[2:3], v[154:155], v[0:1], v[158:159]
	v_pk_fma_f32 v[0:1], v[152:153], v[4:5], v[156:157]
	v_pk_add_f32 v[4:5], v[90:91], v[8:9] op_sel_hi:[1,0] neg_lo:[0,1] neg_hi:[0,1]
	v_pk_mul_f32 v[4:5], v[8:9], v[4:5] op_sel:[1,0]
	s_and_b64 vcc, exec, s[12:13]
	v_pk_fma_f32 v[6:7], v[146:147], v[4:5], v[150:151]
	v_pk_fma_f32 v[4:5], v[144:145], v[10:11], v[148:149]
	v_lshl_add_u64 v[10:11], v[12:13], 2, s[28:29]
	s_cbranch_vccnz .LBB0_740
	global_store_dwordx4 v[10:11], v[0:3], off
	global_store_dwordx4 v[10:11], v[4:7], off offset:16
.LBB0_740:
	v_readlane_b32 s50, v253, 52
	v_readlane_b32 s51, v253, 53
	v_cvt_pk_bf16_f32 v0, v0, v1
	v_cvt_pk_bf16_f32 v1, v2, v3
	v_cvt_pk_bf16_f32 v2, v4, v5
	v_cvt_pk_bf16_f32 v3, v6, v7
	v_lshl_add_u64 v[12:13], v[12:13], 1, s[50:51]
	v_mov_b32_e32 v14, v9
	v_mov_b32_e32 v15, v9
	global_store_dwordx4 v[12:13], v[0:3], off
	v_mov_b32_e32 v6, v9
	v_mov_b32_e32 v7, v9
	v_pk_add_f32 v[0:1], v[86:87], v[8:9] op_sel_hi:[1,0] neg_lo:[0,1] neg_hi:[0,1]
	v_pk_add_f32 v[2:3], v[84:85], v[8:9] op_sel_hi:[1,0] neg_lo:[0,1] neg_hi:[0,1]
	v_pk_mul_f32 v[4:5], v[14:15], v[2:3]
	v_pk_mul_f32 v[0:1], v[6:7], v[0:1]
	v_sub_f32_e32 v9, v81, v8
	v_pk_fma_f32 v[2:3], v[138:139], v[0:1], v[142:143]
	v_pk_fma_f32 v[0:1], v[136:137], v[4:5], v[140:141]
	v_pk_add_f32 v[4:5], v[82:83], v[8:9] op_sel_hi:[1,0] neg_lo:[0,1] neg_hi:[0,1]
	v_sub_f32_e32 v8, v80, v8
	v_pk_mul_f32 v[8:9], v[14:15], v[8:9]
	v_pk_mul_f32 v[4:5], v[6:7], v[4:5]
	s_and_b64 vcc, exec, s[12:13]
	v_pk_fma_f32 v[6:7], v[130:131], v[4:5], v[134:135]
	v_pk_fma_f32 v[4:5], v[128:129], v[8:9], v[132:133]
	s_cbranch_vccnz .LBB0_742
	global_store_dwordx4 v[10:11], v[0:3], off offset:512
	global_store_dwordx4 v[10:11], v[4:7], off offset:528
.LBB0_742:
	ds_read_b64 v[8:9], v219
	v_cvt_pk_bf16_f32 v0, v0, v1
	v_cvt_pk_bf16_f32 v1, v2, v3
	v_cvt_pk_bf16_f32 v2, v4, v5
	v_cvt_pk_bf16_f32 v3, v6, v7
	global_store_dwordx4 v[12:13], v[0:3], off offset:256
	s_waitcnt lgkmcnt(0)
	v_pk_add_f32 v[6:7], v[64:65], v[8:9] op_sel_hi:[1,0] neg_lo:[0,1] neg_hi:[0,1]
	v_add_u32_e32 v0, s54, v218
	v_ashrrev_i32_e32 v1, 31, v0
	v_lshlrev_b64 v[0:1], 10, v[0:1]
	v_lshl_add_u64 v[12:13], v[0:1], 0, v[186:187]
	v_pk_add_f32 v[0:1], v[78:79], v[8:9] op_sel_hi:[1,0] neg_lo:[0,1] neg_hi:[0,1]
	v_pk_add_f32 v[2:3], v[76:77], v[8:9] op_sel_hi:[1,0] neg_lo:[0,1] neg_hi:[0,1]
	v_pk_mul_f32 v[4:5], v[8:9], v[2:3] op_sel:[1,0]
	v_pk_mul_f32 v[0:1], v[8:9], v[0:1] op_sel:[1,0]
	v_pk_mul_f32 v[10:11], v[8:9], v[6:7] op_sel:[1,0]
	v_pk_fma_f32 v[2:3], v[154:155], v[0:1], v[158:159]
	v_pk_fma_f32 v[0:1], v[152:153], v[4:5], v[156:157]
	v_pk_add_f32 v[4:5], v[66:67], v[8:9] op_sel_hi:[1,0] neg_lo:[0,1] neg_hi:[0,1]
	v_pk_mul_f32 v[4:5], v[8:9], v[4:5] op_sel:[1,0]
	s_and_b64 vcc, exec, s[12:13]
	v_pk_fma_f32 v[6:7], v[146:147], v[4:5], v[150:151]
	v_pk_fma_f32 v[4:5], v[144:145], v[10:11], v[148:149]
	v_lshl_add_u64 v[10:11], v[12:13], 2, s[28:29]
	s_cbranch_vccnz .LBB0_744
	global_store_dwordx4 v[10:11], v[0:3], off
	global_store_dwordx4 v[10:11], v[4:7], off offset:16
.LBB0_744:
	v_readlane_b32 s50, v253, 52
	v_readlane_b32 s51, v253, 53
	v_cvt_pk_bf16_f32 v0, v0, v1
	v_cvt_pk_bf16_f32 v1, v2, v3
	v_cvt_pk_bf16_f32 v2, v4, v5
	v_cvt_pk_bf16_f32 v3, v6, v7
	v_lshl_add_u64 v[12:13], v[12:13], 1, s[50:51]
	v_mov_b32_e32 v14, v9
	v_mov_b32_e32 v15, v9
	global_store_dwordx4 v[12:13], v[0:3], off
	v_mov_b32_e32 v6, v9
	v_mov_b32_e32 v7, v9
	v_pk_add_f32 v[0:1], v[54:55], v[8:9] op_sel_hi:[1,0] neg_lo:[0,1] neg_hi:[0,1]
	v_pk_add_f32 v[2:3], v[52:53], v[8:9] op_sel_hi:[1,0] neg_lo:[0,1] neg_hi:[0,1]
	v_pk_mul_f32 v[4:5], v[14:15], v[2:3]
	v_pk_mul_f32 v[0:1], v[6:7], v[0:1]
	v_sub_f32_e32 v9, v49, v8
	v_pk_fma_f32 v[2:3], v[138:139], v[0:1], v[142:143]
	v_pk_fma_f32 v[0:1], v[136:137], v[4:5], v[140:141]
	v_pk_add_f32 v[4:5], v[50:51], v[8:9] op_sel_hi:[1,0] neg_lo:[0,1] neg_hi:[0,1]
	v_sub_f32_e32 v8, v48, v8
	v_pk_mul_f32 v[8:9], v[14:15], v[8:9]
	v_pk_mul_f32 v[4:5], v[6:7], v[4:5]
	s_and_b64 vcc, exec, s[12:13]
	v_pk_fma_f32 v[6:7], v[130:131], v[4:5], v[134:135]
	v_pk_fma_f32 v[4:5], v[128:129], v[8:9], v[132:133]
	s_cbranch_vccnz .LBB0_746
	global_store_dwordx4 v[10:11], v[0:3], off offset:512
	global_store_dwordx4 v[10:11], v[4:7], off offset:528
.LBB0_746:
	ds_read_b64 v[8:9], v221
	v_cvt_pk_bf16_f32 v0, v0, v1
	v_cvt_pk_bf16_f32 v1, v2, v3
	v_cvt_pk_bf16_f32 v2, v4, v5
	v_cvt_pk_bf16_f32 v3, v6, v7
	global_store_dwordx4 v[12:13], v[0:3], off offset:256
	s_waitcnt lgkmcnt(0)
	v_pk_add_f32 v[6:7], v[112:113], v[8:9] op_sel_hi:[1,0] neg_lo:[0,1] neg_hi:[0,1]
	v_add_u32_e32 v0, s54, v220
	v_ashrrev_i32_e32 v1, 31, v0
	v_lshlrev_b64 v[0:1], 10, v[0:1]
	v_lshl_add_u64 v[12:13], v[0:1], 0, v[186:187]
	v_pk_add_f32 v[0:1], v[122:123], v[8:9] op_sel_hi:[1,0] neg_lo:[0,1] neg_hi:[0,1]
	v_pk_add_f32 v[2:3], v[120:121], v[8:9] op_sel_hi:[1,0] neg_lo:[0,1] neg_hi:[0,1]
	v_pk_mul_f32 v[4:5], v[8:9], v[2:3] op_sel:[1,0]
	v_pk_mul_f32 v[0:1], v[8:9], v[0:1] op_sel:[1,0]
	v_pk_mul_f32 v[10:11], v[8:9], v[6:7] op_sel:[1,0]
	v_pk_fma_f32 v[2:3], v[154:155], v[0:1], v[158:159]
	v_pk_fma_f32 v[0:1], v[152:153], v[4:5], v[156:157]
	v_pk_add_f32 v[4:5], v[114:115], v[8:9] op_sel_hi:[1,0] neg_lo:[0,1] neg_hi:[0,1]
	v_pk_mul_f32 v[4:5], v[8:9], v[4:5] op_sel:[1,0]
	s_and_b64 vcc, exec, s[12:13]
	v_pk_fma_f32 v[6:7], v[146:147], v[4:5], v[150:151]
	v_pk_fma_f32 v[4:5], v[144:145], v[10:11], v[148:149]
	v_lshl_add_u64 v[10:11], v[12:13], 2, s[28:29]
	s_cbranch_vccnz .LBB0_748
	global_store_dwordx4 v[10:11], v[0:3], off
	global_store_dwordx4 v[10:11], v[4:7], off offset:16
.LBB0_748:
	v_readlane_b32 s50, v253, 52
	v_readlane_b32 s51, v253, 53
	v_cvt_pk_bf16_f32 v0, v0, v1
	v_cvt_pk_bf16_f32 v1, v2, v3
	v_cvt_pk_bf16_f32 v2, v4, v5
	v_cvt_pk_bf16_f32 v3, v6, v7
	v_lshl_add_u64 v[12:13], v[12:13], 1, s[50:51]
	v_mov_b32_e32 v14, v9
	v_mov_b32_e32 v15, v9
	global_store_dwordx4 v[12:13], v[0:3], off
	v_mov_b32_e32 v6, v9
	v_mov_b32_e32 v7, v9
	v_pk_add_f32 v[0:1], v[102:103], v[8:9] op_sel_hi:[1,0] neg_lo:[0,1] neg_hi:[0,1]
	v_pk_add_f32 v[2:3], v[100:101], v[8:9] op_sel_hi:[1,0] neg_lo:[0,1] neg_hi:[0,1]
	v_pk_mul_f32 v[4:5], v[14:15], v[2:3]
	v_pk_mul_f32 v[0:1], v[6:7], v[0:1]
	v_sub_f32_e32 v9, v125, v8
	v_pk_fma_f32 v[2:3], v[138:139], v[0:1], v[142:143]
	v_pk_fma_f32 v[0:1], v[136:137], v[4:5], v[140:141]
	v_pk_add_f32 v[4:5], v[126:127], v[8:9] op_sel_hi:[1,0] neg_lo:[0,1] neg_hi:[0,1]
	v_sub_f32_e32 v8, v124, v8
	v_pk_mul_f32 v[8:9], v[14:15], v[8:9]
	v_pk_mul_f32 v[4:5], v[6:7], v[4:5]
	s_and_b64 vcc, exec, s[12:13]
	v_pk_fma_f32 v[6:7], v[130:131], v[4:5], v[134:135]
	v_pk_fma_f32 v[4:5], v[128:129], v[8:9], v[132:133]
	s_cbranch_vccnz .LBB0_750
	global_store_dwordx4 v[10:11], v[0:3], off offset:512
	global_store_dwordx4 v[10:11], v[4:7], off offset:528
.LBB0_750:
	ds_read_b64 v[8:9], v223
	v_cvt_pk_bf16_f32 v0, v0, v1
	v_cvt_pk_bf16_f32 v1, v2, v3
	v_cvt_pk_bf16_f32 v2, v4, v5
	v_cvt_pk_bf16_f32 v3, v6, v7
	global_store_dwordx4 v[12:13], v[0:3], off offset:256
	s_waitcnt lgkmcnt(0)
	v_pk_add_f32 v[6:7], v[108:109], v[8:9] op_sel_hi:[1,0] neg_lo:[0,1] neg_hi:[0,1]
	v_add_u32_e32 v0, s54, v222
	v_ashrrev_i32_e32 v1, 31, v0
	v_lshlrev_b64 v[0:1], 10, v[0:1]
	v_lshl_add_u64 v[12:13], v[0:1], 0, v[186:187]
	v_pk_add_f32 v[0:1], v[118:119], v[8:9] op_sel_hi:[1,0] neg_lo:[0,1] neg_hi:[0,1]
	v_pk_add_f32 v[2:3], v[116:117], v[8:9] op_sel_hi:[1,0] neg_lo:[0,1] neg_hi:[0,1]
	v_pk_mul_f32 v[4:5], v[8:9], v[2:3] op_sel:[1,0]
	v_pk_mul_f32 v[0:1], v[8:9], v[0:1] op_sel:[1,0]
	v_pk_mul_f32 v[10:11], v[8:9], v[6:7] op_sel:[1,0]
	v_pk_fma_f32 v[2:3], v[154:155], v[0:1], v[158:159]
	v_pk_fma_f32 v[0:1], v[152:153], v[4:5], v[156:157]
	v_pk_add_f32 v[4:5], v[110:111], v[8:9] op_sel_hi:[1,0] neg_lo:[0,1] neg_hi:[0,1]
	v_pk_mul_f32 v[4:5], v[8:9], v[4:5] op_sel:[1,0]
	s_and_b64 vcc, exec, s[12:13]
	v_pk_fma_f32 v[6:7], v[146:147], v[4:5], v[150:151]
	v_pk_fma_f32 v[4:5], v[144:145], v[10:11], v[148:149]
	v_lshl_add_u64 v[10:11], v[12:13], 2, s[28:29]
	s_cbranch_vccnz .LBB0_752
	global_store_dwordx4 v[10:11], v[0:3], off
	global_store_dwordx4 v[10:11], v[4:7], off offset:16
.LBB0_752:
	v_readlane_b32 s50, v253, 52
	v_readlane_b32 s51, v253, 53
	v_cvt_pk_bf16_f32 v0, v0, v1
	v_cvt_pk_bf16_f32 v1, v2, v3
	v_cvt_pk_bf16_f32 v2, v4, v5
	v_cvt_pk_bf16_f32 v3, v6, v7
	v_lshl_add_u64 v[12:13], v[12:13], 1, s[50:51]
	v_mov_b32_e32 v14, v9
	v_mov_b32_e32 v15, v9
	global_store_dwordx4 v[12:13], v[0:3], off
	v_mov_b32_e32 v6, v9
	v_mov_b32_e32 v7, v9
	v_pk_add_f32 v[0:1], v[98:99], v[8:9] op_sel_hi:[1,0] neg_lo:[0,1] neg_hi:[0,1]
	v_pk_add_f32 v[2:3], v[96:97], v[8:9] op_sel_hi:[1,0] neg_lo:[0,1] neg_hi:[0,1]
	v_pk_mul_f32 v[4:5], v[14:15], v[2:3]
	v_pk_mul_f32 v[0:1], v[6:7], v[0:1]
	v_sub_f32_e32 v9, v105, v8
	v_pk_fma_f32 v[2:3], v[138:139], v[0:1], v[142:143]
	v_pk_fma_f32 v[0:1], v[136:137], v[4:5], v[140:141]
	v_pk_add_f32 v[4:5], v[106:107], v[8:9] op_sel_hi:[1,0] neg_lo:[0,1] neg_hi:[0,1]
	v_sub_f32_e32 v8, v104, v8
	v_pk_mul_f32 v[8:9], v[14:15], v[8:9]
	v_pk_mul_f32 v[4:5], v[6:7], v[4:5]
	s_and_b64 vcc, exec, s[12:13]
	v_pk_fma_f32 v[6:7], v[130:131], v[4:5], v[134:135]
	v_pk_fma_f32 v[4:5], v[128:129], v[8:9], v[132:133]
	s_cbranch_vccnz .LBB0_754
	global_store_dwordx4 v[10:11], v[0:3], off offset:512
	global_store_dwordx4 v[10:11], v[4:7], off offset:528
